# cand34 with the P2 sample-row tail's first four prefetch sets requested before the tail's first wait
# speedup vs baseline: 1.0066x; 1.0066x over previous
.LBB0_601:
	s_ashr_i32 s0, s25, 6
	s_add_i32 s2, s0, s81
	s_cmp_gt_i32 s2, 31
	s_cbranch_scc1 .LBB0_603
	s_ashr_i32 s3, s2, 31
	s_lshl_b64 s[0:1], s[2:3], 15
	v_and_b32_e32 v1, 63, v1
	s_waitcnt lgkmcnt(0)
	s_add_u32 s0, s14, s0
	s_waitcnt vmcnt(3)
	v_mov_b32_e32 v67, 0
	s_addc_u32 s1, s15, s1
	v_lshlrev_b32_e32 v66, 4, v1
	v_lshl_add_u64 v[68:69], s[0:1], 0, v[66:67]
	s_mov_b64 s[0:1], 0x69984000
	v_lshl_add_u64 v[2:3], v[68:69], 0, s[0:1]
	s_mov_b32 s1, 0x69986000
	v_add_co_u32_e32 v4, vcc, s1, v68
	s_mov_b32 s0, 0x69985000
	s_nop 0
	v_addc_co_u32_e32 v5, vcc, 0, v69, vcc
	v_add_co_u32_e32 v6, vcc, s0, v68
	global_load_dwordx4 v[58:61], v[2:3], off offset:1024
	global_load_dwordx4 v[50:53], v[2:3], off offset:2048
	v_addc_co_u32_e32 v7, vcc, 0, v69, vcc
	global_load_dwordx4 v[46:49], v[4:5], off offset:-4096
	global_load_dwordx4 v[42:45], v[6:7], off offset:1024
	global_load_dwordx4 v[38:41], v[6:7], off offset:2048
	global_load_dwordx4 v[34:37], v[6:7], off offset:3072
	v_add_co_u32_e32 v6, vcc, 0x69984000, v68
	global_load_dwordx4 v[30:33], v[4:5], off
	global_load_dwordx4 v[26:29], v[4:5], off offset:1024
	v_addc_co_u32_e32 v7, vcc, 0, v69, vcc
	global_load_dwordx4 v[62:65], v[6:7], off
	global_load_dwordx4 v[54:57], v[2:3], off offset:3072
	global_load_dwordx4 v[22:25], v[4:5], off offset:2048
	s_mov_b32 s0, 0x69987000
	global_load_dwordx4 v[18:21], v[4:5], off offset:3072
	v_add_co_u32_e32 v70, vcc, s0, v68
	s_mov_b32 s0, 0xf800000
	s_nop 0
	v_addc_co_u32_e32 v71, vcc, 0, v69, vcc
	global_load_dwordx4 v[14:17], v[70:71], off
	global_load_dwordx4 v[10:13], v[70:71], off offset:1024
	global_load_dwordx4 v[6:9], v[70:71], off offset:2048
	global_load_dwordx4 v[2:5], v[70:71], off offset:3072
	s_waitcnt vmcnt(15)
	v_mov_b32_e32 v70, v59
	v_mov_b32_e32 v71, v60
	v_mov_b32_e32 v72, v58
	v_mov_b32_e32 v73, v61
	s_waitcnt vmcnt(13)
	v_mov_b32_e32 v78, v47
	v_mov_b32_e32 v79, v48
	v_mov_b32_e32 v80, v46
	v_mov_b32_e32 v81, v49
	s_waitcnt vmcnt(12)
	v_add_f32_e32 v82, v42, v43
	v_add_f32_e32 v84, v44, v45
	s_waitcnt vmcnt(11)
	v_mov_b32_e32 v83, v40
	v_mov_b32_e32 v85, v41
	s_waitcnt vmcnt(10)
	v_mov_b32_e32 v86, v35
	v_mov_b32_e32 v87, v36
	v_mov_b32_e32 v88, v34
	v_mov_b32_e32 v89, v37
	s_waitcnt vmcnt(7)
	v_mov_b32_e32 v94, v63
	v_mov_b32_e32 v95, v64
	v_mov_b32_e32 v96, v62
	v_mov_b32_e32 v97, v65
	v_pk_add_f32 v[70:71], v[70:71], v[72:73]
	v_pk_add_f32 v[78:79], v[78:79], v[80:81]
	v_pk_add_f32 v[80:81], v[82:83], v[84:85]
	v_pk_add_f32 v[82:83], v[86:87], v[88:89]
	v_pk_add_f32 v[86:87], v[94:95], v[96:97]
	v_pk_add_f32 v[70:71], v[70:71], v[70:71] op_sel:[0,1] op_sel_hi:[1,0]
	v_add_f32_e32 v72, v86, v87
	v_add_f32_e32 v74, v50, v51
	v_add_f32_e32 v76, v52, v53
	s_waitcnt vmcnt(6)
	v_mov_b32_e32 v73, v54
	v_mov_b32_e32 v75, v56
	v_mov_b32_e32 v77, v57
	v_mov_b32_e32 v71, v55
	v_add_f32_e32 v72, 0, v72
	v_pk_add_f32 v[74:75], v[74:75], v[76:77]
	v_pk_add_f32 v[70:71], v[72:73], v[70:71]
	v_pk_add_f32 v[76:77], v[78:79], v[78:79] op_sel:[0,1] op_sel_hi:[1,0]
	v_pk_add_f32 v[70:71], v[70:71], v[74:75]
	v_mov_b32_e32 v77, v39
	v_pk_add_f32 v[70:71], v[70:71], v[70:71] op_sel:[0,1] op_sel_hi:[1,0]
	v_pk_add_f32 v[78:79], v[82:83], v[82:83] op_sel:[0,1] op_sel_hi:[1,0]
	v_mov_b32_e32 v71, v38
	v_pk_add_f32 v[70:71], v[70:71], v[76:77]
	v_add_f32_e32 v90, v30, v31
	v_pk_add_f32 v[70:71], v[70:71], v[80:81]
	v_add_f32_e32 v92, v32, v33
	v_pk_add_f32 v[70:71], v[70:71], v[70:71] op_sel:[0,1] op_sel_hi:[1,0]
	v_mov_b32_e32 v91, v28
	v_mov_b32_e32 v93, v29
	v_mov_b32_e32 v79, v27
	v_mov_b32_e32 v71, v26
	v_pk_add_f32 v[84:85], v[90:91], v[92:93]
	v_pk_add_f32 v[70:71], v[70:71], v[78:79]
	s_waitcnt vmcnt(5)
	v_mov_b32_e32 v72, v23
	v_mov_b32_e32 v73, v24
	v_mov_b32_e32 v74, v22
	v_mov_b32_e32 v75, v25
	v_pk_add_f32 v[70:71], v[70:71], v[84:85]
	v_pk_add_f32 v[72:73], v[72:73], v[74:75]
	v_pk_add_f32 v[70:71], v[70:71], v[70:71] op_sel:[0,1] op_sel_hi:[1,0]
	v_pk_add_f32 v[72:73], v[72:73], v[72:73] op_sel:[0,1] op_sel_hi:[1,0]
	s_waitcnt vmcnt(4)
	v_add_f32_e32 v74, v18, v19
	v_add_f32_e32 v76, v20, v21
	s_waitcnt vmcnt(3)
	v_mov_b32_e32 v71, v14
	v_mov_b32_e32 v73, v15
	v_mov_b32_e32 v75, v16
	v_mov_b32_e32 v77, v17
	v_pk_add_f32 v[70:71], v[70:71], v[72:73]
	v_pk_add_f32 v[72:73], v[74:75], v[76:77]
	s_waitcnt vmcnt(2)
	v_mov_b32_e32 v74, v10
	v_pk_add_f32 v[70:71], v[70:71], v[72:73]
	v_mov_b32_e32 v72, v11
	v_mov_b32_e32 v73, v12
	v_mov_b32_e32 v75, v13
	v_pk_add_f32 v[72:73], v[72:73], v[74:75]
	v_pk_add_f32 v[70:71], v[70:71], v[70:71] op_sel:[0,1] op_sel_hi:[1,0]
	v_pk_add_f32 v[72:73], v[72:73], v[72:73] op_sel:[0,1] op_sel_hi:[1,0]
	s_waitcnt vmcnt(1)
	v_add_f32_e32 v74, v6, v7
	v_add_f32_e32 v76, v8, v9
	s_waitcnt vmcnt(0)
	v_mov_b32_e32 v71, v2
	v_mov_b32_e32 v73, v3
	v_mov_b32_e32 v75, v4
	v_mov_b32_e32 v77, v5
	v_pk_add_f32 v[70:71], v[70:71], v[72:73]
	v_pk_add_f32 v[72:73], v[74:75], v[76:77]
	s_nop 0
	v_pk_add_f32 v[70:71], v[70:71], v[72:73]
	s_nop 0
	v_add_f32_e32 v70, v70, v71
	v_mbcnt_hi_u32_b32 v71, -1, v234
	v_and_b32_e32 v72, 64, v71
	v_add_u32_e32 v72, 64, v72
	v_xor_b32_e32 v73, 1, v71
	v_cmp_lt_i32_e32 vcc, v73, v72
	s_nop 1
	v_cndmask_b32_e32 v73, v71, v73, vcc
	v_lshlrev_b32_e32 v78, 2, v73
	s_waitcnt lgkmcnt(0)
	s_nop 1
	v_add_f32_dpp v70, v70, v70 quad_perm:[1,0,3,2] row_mask:0xf bank_mask:0xf
	v_xor_b32_e32 v73, 2, v71
	v_cmp_lt_i32_e32 vcc, v73, v72
	s_nop 1
	v_cndmask_b32_e32 v73, v71, v73, vcc
	v_lshlrev_b32_e32 v84, 2, v73
	s_waitcnt lgkmcnt(0)
	s_nop 1
	v_add_f32_dpp v70, v70, v70 quad_perm:[2,3,0,1] row_mask:0xf bank_mask:0xf
	v_xor_b32_e32 v73, 4, v71
	v_cmp_lt_i32_e32 vcc, v73, v72
	s_nop 1
	v_cndmask_b32_e32 v73, v71, v73, vcc
	v_lshlrev_b32_e32 v85, 2, v73
	s_waitcnt lgkmcnt(0)
	s_nop 1
	v_add_f32_dpp v70, v70, v70 row_half_mirror row_mask:0xf bank_mask:0xf
	v_xor_b32_e32 v73, 8, v71
	v_cmp_lt_i32_e32 vcc, v73, v72
	s_nop 1
	v_cndmask_b32_e32 v73, v71, v73, vcc
	v_lshlrev_b32_e32 v86, 2, v73
	s_waitcnt lgkmcnt(0)
	s_nop 1
	v_add_f32_dpp v70, v70, v70 row_mirror row_mask:0xf bank_mask:0xf
	v_xor_b32_e32 v73, 16, v71
	v_cmp_lt_i32_e32 vcc, v73, v72
	s_nop 1
	v_cndmask_b32_e32 v73, v71, v73, vcc
	v_lshlrev_b32_e32 v87, 2, v73
	s_waitcnt lgkmcnt(0)
	v_mov_b32_e32 v73, v70
	s_nop 1
	v_permlane16_swap_b32_e32 v73, v70
	v_add_f32_e32 v70, v70, v73
	v_xor_b32_e32 v73, 32, v71
	v_cmp_lt_i32_e32 vcc, v73, v72
	s_nop 1
	v_cndmask_b32_e32 v71, v71, v73, vcc
	v_lshlrev_b32_e32 v88, 2, v71
	s_waitcnt lgkmcnt(0)
	v_mov_b32_e32 v79, v70
	v_mov_b32_e32 v71, v70
	s_nop 1
	v_permlane32_swap_b32_e32 v71, v79
	v_add_f32_e32 v79, v79, v71
	v_fmamk_f32 v75, v79, 0xb9800000, v63
	v_fmamk_f32 v74, v79, 0xb9800000, v62
	v_fmamk_f32 v65, v79, 0xb9800000, v65
	v_fmac_f32_e32 v64, 0xb9800000, v79
	v_pk_mul_f32 v[62:63], v[64:65], v[64:65]
	v_pk_mul_f32 v[70:71], v[74:75], v[74:75]
	v_fmamk_f32 v61, v79, 0xb9800000, v61
	v_pk_mov_b32 v[72:73], v[70:71], v[62:63] op_sel:[1,0]
	v_mov_b32_e32 v71, v63
	v_pk_add_f32 v[62:63], v[72:73], v[70:71]
	v_fmamk_f32 v73, v79, 0xb9800000, v59
	v_fmamk_f32 v72, v79, 0xb9800000, v58
	v_fmac_f32_e32 v60, 0xb9800000, v79
	v_pk_mul_f32 v[58:59], v[60:61], v[60:61]
	v_pk_mul_f32 v[70:71], v[72:73], v[72:73]
	v_fmac_f32_e32 v54, 0xb9800000, v79
	v_pk_mov_b32 v[76:77], v[70:71], v[58:59] op_sel:[1,0]
	v_mov_b32_e32 v71, v59
	v_pk_add_f32 v[76:77], v[76:77], v[70:71]
	v_fmamk_f32 v71, v79, 0xb9800000, v51
	v_fmamk_f32 v70, v79, 0xb9800000, v50
	v_fmamk_f32 v58, v79, 0xb9800000, v56
	v_fmamk_f32 v55, v79, 0xb9800000, v55
	v_mul_f32_e32 v56, v54, v54
	v_pk_add_f32 v[50:51], v[62:63], v[62:63] op_sel:[0,1] op_sel_hi:[1,0]
	v_fmamk_f32 v59, v79, 0xb9800000, v57
	v_mul_f32_e32 v80, v55, v55
	v_mov_b32_e32 v51, v56
	v_pk_add_f32 v[56:57], v[76:77], v[76:77] op_sel:[0,1] op_sel_hi:[1,0]
	v_fmamk_f32 v53, v79, 0xb9800000, v53
	v_mov_b32_e32 v57, v80
	v_fmac_f32_e32 v52, 0xb9800000, v79
	v_pk_add_f32 v[50:51], v[50:51], v[56:57]
	v_mul_f32_e32 v56, v71, v71
	v_mul_f32_e32 v62, v53, v53
	v_mul_f32_e32 v81, v58, v58
	v_mul_f32_e32 v82, v59, v59
	v_pk_fma_f32 v[56:57], v[70:71], v[70:71], v[56:57] op_sel_hi:[1,1,0]
	v_pk_fma_f32 v[62:63], v[52:53], v[52:53], v[62:63] op_sel_hi:[1,1,0]
	v_mov_b32_e32 v57, v81
	v_mov_b32_e32 v63, v82
	v_pk_add_f32 v[56:57], v[56:57], v[62:63]
	v_fmamk_f32 v49, v79, 0xb9800000, v49
	v_pk_add_f32 v[62:63], v[50:51], v[56:57]
	v_fmamk_f32 v57, v79, 0xb9800000, v47
	v_fmamk_f32 v56, v79, 0xb9800000, v46
	v_fmac_f32_e32 v48, 0xb9800000, v79
	v_pk_mul_f32 v[46:47], v[48:49], v[48:49]
	v_pk_mul_f32 v[50:51], v[56:57], v[56:57]
	v_fmac_f32_e32 v38, 0xb9800000, v79
	v_pk_mov_b32 v[76:77], v[50:51], v[46:47] op_sel:[1,0]
	v_mov_b32_e32 v51, v47
	v_pk_add_f32 v[76:77], v[76:77], v[50:51]
	v_fmamk_f32 v50, v79, 0xb9800000, v42
	v_fmamk_f32 v47, v79, 0xb9800000, v41
	v_fmamk_f32 v46, v79, 0xb9800000, v40
	v_fmamk_f32 v39, v79, 0xb9800000, v39
	v_mul_f32_e32 v42, v38, v38
	v_pk_add_f32 v[40:41], v[62:63], v[62:63] op_sel:[0,1] op_sel_hi:[1,0]
	v_fmamk_f32 v51, v79, 0xb9800000, v43
	v_mul_f32_e32 v80, v39, v39
	v_mov_b32_e32 v41, v42
	v_pk_add_f32 v[42:43], v[76:77], v[76:77] op_sel:[0,1] op_sel_hi:[1,0]
	v_fmamk_f32 v45, v79, 0xb9800000, v45
	v_mov_b32_e32 v43, v80
	v_fmac_f32_e32 v44, 0xb9800000, v79
	v_pk_add_f32 v[40:41], v[40:41], v[42:43]
	v_mul_f32_e32 v42, v51, v51
	v_mul_f32_e32 v62, v45, v45
	v_mul_f32_e32 v81, v46, v46
	v_mul_f32_e32 v82, v47, v47
	v_pk_fma_f32 v[42:43], v[50:51], v[50:51], v[42:43] op_sel_hi:[1,1,0]
	v_pk_fma_f32 v[62:63], v[44:45], v[44:45], v[62:63] op_sel_hi:[1,1,0]
	v_mov_b32_e32 v43, v81
	v_mov_b32_e32 v63, v82
	v_pk_add_f32 v[42:43], v[42:43], v[62:63]
	v_fmamk_f32 v37, v79, 0xb9800000, v37
	v_pk_add_f32 v[62:63], v[40:41], v[42:43]
	v_fmamk_f32 v43, v79, 0xb9800000, v35
	v_fmamk_f32 v42, v79, 0xb9800000, v34
	v_fmac_f32_e32 v36, 0xb9800000, v79
	v_pk_mul_f32 v[34:35], v[36:37], v[36:37]
	v_pk_mul_f32 v[40:41], v[42:43], v[42:43]
	v_fmac_f32_e32 v26, 0xb9800000, v79
	v_pk_mov_b32 v[76:77], v[40:41], v[34:35] op_sel:[1,0]
	v_mov_b32_e32 v41, v35
	v_pk_add_f32 v[76:77], v[76:77], v[40:41]
	v_fmamk_f32 v40, v79, 0xb9800000, v30
	v_fmamk_f32 v35, v79, 0xb9800000, v29
	v_fmamk_f32 v34, v79, 0xb9800000, v28
	v_fmamk_f32 v27, v79, 0xb9800000, v27
	v_mul_f32_e32 v30, v26, v26
	v_pk_add_f32 v[28:29], v[62:63], v[62:63] op_sel:[0,1] op_sel_hi:[1,0]
	v_fmamk_f32 v41, v79, 0xb9800000, v31
	v_mul_f32_e32 v80, v27, v27
	v_mov_b32_e32 v29, v30
	v_pk_add_f32 v[30:31], v[76:77], v[76:77] op_sel:[0,1] op_sel_hi:[1,0]
	v_fmamk_f32 v33, v79, 0xb9800000, v33
	v_mov_b32_e32 v31, v80
	v_fmac_f32_e32 v32, 0xb9800000, v79
	v_pk_add_f32 v[28:29], v[28:29], v[30:31]
	v_mul_f32_e32 v30, v41, v41
	v_mul_f32_e32 v62, v33, v33
	v_mul_f32_e32 v81, v34, v34
	v_mul_f32_e32 v82, v35, v35
	v_pk_fma_f32 v[30:31], v[40:41], v[40:41], v[30:31] op_sel_hi:[1,1,0]
	v_pk_fma_f32 v[62:63], v[32:33], v[32:33], v[62:63] op_sel_hi:[1,1,0]
	v_mov_b32_e32 v31, v81
	v_mov_b32_e32 v63, v82
	v_pk_add_f32 v[30:31], v[30:31], v[62:63]
	v_fmamk_f32 v25, v79, 0xb9800000, v25
	v_pk_add_f32 v[28:29], v[28:29], v[30:31]
	v_fmamk_f32 v31, v79, 0xb9800000, v23
	v_fmamk_f32 v30, v79, 0xb9800000, v22
	v_fmac_f32_e32 v24, 0xb9800000, v79
	v_pk_mul_f32 v[22:23], v[24:25], v[24:25]
	v_pk_mul_f32 v[62:63], v[30:31], v[30:31]
	v_fmamk_f32 v15, v79, 0xb9800000, v15
	v_pk_mov_b32 v[76:77], v[62:63], v[22:23] op_sel:[1,0]
	v_mov_b32_e32 v63, v23
	v_pk_add_f32 v[62:63], v[76:77], v[62:63]
	v_fmac_f32_e32 v14, 0xb9800000, v79
	v_fmamk_f32 v23, v79, 0xb9800000, v19
	v_fmamk_f32 v22, v79, 0xb9800000, v18
	v_mul_f32_e32 v76, v14, v14
	v_mul_f32_e32 v77, v15, v15
	v_pk_add_f32 v[18:19], v[28:29], v[28:29] op_sel:[0,1] op_sel_hi:[1,0]
	v_pk_add_f32 v[28:29], v[62:63], v[62:63] op_sel:[0,1] op_sel_hi:[1,0]
	v_fmamk_f32 v21, v79, 0xb9800000, v21
	v_mov_b32_e32 v19, v76
	v_mov_b32_e32 v29, v77
	v_fmac_f32_e32 v20, 0xb9800000, v79
	v_fmamk_f32 v17, v79, 0xb9800000, v17
	v_fmamk_f32 v16, v79, 0xb9800000, v16
	v_pk_add_f32 v[18:19], v[18:19], v[28:29]
	v_mul_f32_e32 v28, v23, v23
	v_mul_f32_e32 v62, v21, v21
	v_mul_f32_e32 v80, v16, v16
	v_mul_f32_e32 v81, v17, v17
	v_pk_fma_f32 v[28:29], v[22:23], v[22:23], v[28:29] op_sel_hi:[1,1,0]
	v_pk_fma_f32 v[62:63], v[20:21], v[20:21], v[62:63] op_sel_hi:[1,1,0]
	v_mov_b32_e32 v29, v80
	v_mov_b32_e32 v63, v81
	v_pk_add_f32 v[28:29], v[28:29], v[62:63]
	v_fmamk_f32 v11, v79, 0xb9800000, v11
	v_fmamk_f32 v10, v79, 0xb9800000, v10
	v_fmamk_f32 v13, v79, 0xb9800000, v13
	v_fmac_f32_e32 v12, 0xb9800000, v79
	v_pk_add_f32 v[18:19], v[18:19], v[28:29]
	v_pk_mul_f32 v[28:29], v[12:13], v[12:13]
	v_pk_mul_f32 v[62:63], v[10:11], v[10:11]
	v_fmamk_f32 v3, v79, 0xb9800000, v3
	v_pk_mov_b32 v[76:77], v[62:63], v[28:29] op_sel:[1,0]
	v_mov_b32_e32 v63, v29
	v_pk_add_f32 v[28:29], v[76:77], v[62:63]
	v_fmac_f32_e32 v2, 0xb9800000, v79
	v_mul_f32_e32 v62, v2, v2
	v_mul_f32_e32 v63, v3, v3
	v_pk_add_f32 v[18:19], v[18:19], v[18:19] op_sel:[0,1] op_sel_hi:[1,0]
	v_pk_add_f32 v[28:29], v[28:29], v[28:29] op_sel:[0,1] op_sel_hi:[1,0]
	v_fmamk_f32 v7, v79, 0xb9800000, v7
	v_fmamk_f32 v9, v79, 0xb9800000, v9
	v_mov_b32_e32 v19, v62
	v_mov_b32_e32 v29, v63
	v_fmamk_f32 v6, v79, 0xb9800000, v6
	v_fmac_f32_e32 v8, 0xb9800000, v79
	v_fmamk_f32 v5, v79, 0xb9800000, v5
	v_fmamk_f32 v4, v79, 0xb9800000, v4
	v_pk_add_f32 v[18:19], v[18:19], v[28:29]
	v_mul_f32_e32 v28, v7, v7
	v_mul_f32_e32 v62, v9, v9
	v_mul_f32_e32 v76, v4, v4
	v_mul_f32_e32 v77, v5, v5
	v_pk_fma_f32 v[28:29], v[6:7], v[6:7], v[28:29] op_sel_hi:[1,1,0]
	v_pk_fma_f32 v[62:63], v[8:9], v[8:9], v[62:63] op_sel_hi:[1,1,0]
	v_mov_b32_e32 v29, v76
	v_mov_b32_e32 v63, v77
	v_pk_add_f32 v[28:29], v[28:29], v[62:63]
	s_nop 0
	v_pk_add_f32 v[18:19], v[18:19], v[28:29]
	s_nop 0
	v_add_f32_e32 v18, v18, v19
	global_load_dwordx4 v[76:79], v66, s[4:5]
	global_load_dwordx4 v[80:83], v66, s[6:7]
	s_mov_b64 s[100:101], 0x69981000
	v_lshl_add_u64 v[238:239], v[68:69], 0, s[100:101]
	s_mov_b64 s[98:99], 0x2000
	v_lshl_add_u64 v[240:241], v[238:239], 0, s[98:99]
	v_add_u32_e32 v235, 0x400, v66
	global_load_dwordx4 v[192:195], v235, s[4:5]
	global_load_dwordx4 v[196:199], v235, s[6:7]
	v_mov_b32_e32 v236, 0x10000
	global_load_dword v204, v236, s[8:9]
	global_load_dword v205, v67, s[10:11] offset:512
	global_load_dwordx4 v[200:203], v[238:239], off offset:-3072
	v_add_u32_e32 v235, 0x800, v66
	global_load_dwordx4 v[206:209], v235, s[4:5]
	global_load_dwordx4 v[210:213], v235, s[6:7]
	v_mov_b32_e32 v236, 0x20000
	global_load_dword v218, v236, s[8:9]
	global_load_dword v219, v67, s[10:11] offset:1024
	global_load_dwordx4 v[214:217], v[238:239], off offset:-2048
	v_add_u32_e32 v235, 0xc00, v66
	global_load_dwordx4 v[220:223], v235, s[4:5]
	global_load_dwordx4 v[224:227], v235, s[6:7]
	v_mov_b32_e32 v236, 0x30000
	global_load_dword v232, v236, s[8:9]
	global_load_dword v233, v67, s[10:11] offset:1536
	global_load_dwordx4 v[228:231], v[238:239], off offset:-1024
	v_add_u32_e32 v235, 0x1000, v66
	global_load_dwordx4 v[178:181], v235, s[4:5]
	global_load_dwordx4 v[182:185], v235, s[6:7]
	v_mov_b32_e32 v236, 0x40000
	global_load_dword v190, v236, s[8:9]
	global_load_dword v191, v67, s[10:11] offset:2048
	global_load_dwordx4 v[186:189], v[238:239], off offset:0
	s_waitcnt lgkmcnt(0)
	s_nop 1
	v_add_f32_dpp v18, v18, v18 quad_perm:[1,0,3,2] row_mask:0xf bank_mask:0xf
	s_waitcnt lgkmcnt(0)
	s_nop 1
	v_add_f32_dpp v18, v18, v18 quad_perm:[2,3,0,1] row_mask:0xf bank_mask:0xf
	s_waitcnt lgkmcnt(0)
	s_nop 1
	v_add_f32_dpp v18, v18, v18 row_half_mirror row_mask:0xf bank_mask:0xf
	v_lshlrev_b32_e32 v86, 3, v1
	v_mov_b32_e32 v1, 0x10000
	s_waitcnt lgkmcnt(0)
	s_nop 1
	v_add_f32_dpp v18, v18, v18 row_mirror row_mask:0xf bank_mask:0xf
	v_mov_b32_e32 v87, v67
	s_waitcnt lgkmcnt(0)
	v_mov_b32_e32 v19, v18
	s_nop 1
	v_permlane16_swap_b32_e32 v19, v18
	v_add_f32_e32 v18, v18, v19
	s_waitcnt lgkmcnt(0)
	v_mov_b32_e32 v19, v18
	s_nop 1
	v_permlane32_swap_b32_e32 v19, v18
	v_add_f32_e32 v18, v18, v19
	v_mov_b32_e32 v19, 0x358637bd
	v_fmac_f32_e32 v19, 0x39800000, v18
	v_mul_f32_e32 v18, 0x4f800000, v19
	v_cmp_gt_f32_e32 vcc, s0, v19
	s_nop 1
	v_cndmask_b32_e32 v18, v19, v18, vcc
	v_sqrt_f32_e32 v19, v18
	s_nop 0
	v_add_u32_e32 v28, -1, v19
	v_fma_f32 v29, -v28, v19, v18
	v_cmp_ge_f32_e64 s[0:1], 0, v29
	v_add_u32_e32 v29, 1, v19
	s_nop 0
	v_cndmask_b32_e64 v28, v19, v28, s[0:1]
	v_fma_f32 v19, -v29, v19, v18
	v_cmp_lt_f32_e64 s[0:1], 0, v19
	s_nop 1
	v_cndmask_b32_e64 v19, v28, v29, s[0:1]
	v_mul_f32_e32 v28, 0x37800000, v19
	v_cndmask_b32_e32 v19, v19, v28, vcc
	v_mov_b32_e32 v28, 0x260
	v_cmp_class_f32_e32 vcc, v18, v28
	s_nop 1
	v_cndmask_b32_e32 v18, v19, v18, vcc
	v_div_scale_f32 v19, s[0:1], v18, v18, 1.0
	v_rcp_f32_e32 v28, v19
	s_lshl_b64 s[0:1], s[2:3], 14
	s_add_u32 s0, s12, s0
	s_addc_u32 s1, s13, s1
	v_fma_f32 v29, -v19, v28, 1.0
	v_fmac_f32_e32 v28, v29, v28
	v_div_scale_f32 v29, vcc, 1.0, v18, 1.0
	v_mul_f32_e32 v62, v29, v28
	v_fma_f32 v63, -v19, v62, v29
	v_fmac_f32_e32 v62, v63, v28
	v_fma_f32 v19, -v19, v62, v29
	v_div_fmas_f32 v19, v19, v28, v62
	v_div_fixup_f32 v18, v19, v18, 1.0
	v_lshl_add_u64 v[62:63], s[0:1], 0, v[66:67]
	v_pk_mul_f32 v[64:65], v[18:19], v[64:65] op_sel_hi:[0,1]
	s_mov_b32 s0, 0x8881000
	v_pk_mul_f32 v[28:29], v[18:19], v[74:75] op_sel_hi:[0,1]
	s_waitcnt vmcnt(20)
	v_pk_fma_f32 v[78:79], v[78:79], v[64:65], v[82:83]
	v_add_co_u32_e32 v64, vcc, s0, v62
	v_pk_fma_f32 v[76:77], v[76:77], v[28:29], v[80:81]
	s_nop 0
	v_addc_co_u32_e32 v65, vcc, 0, v63, vcc
	s_mov_b32 s0, 0x69981000
	global_store_dwordx4 v[64:65], v[76:79], off offset:-4096
	v_add_co_u32_e32 v74, vcc, s0, v68
	global_load_dword v28, v67, s[8:9]
	global_load_dword v84, v67, s[10:11]
	v_addc_co_u32_e32 v75, vcc, 0, v69, vcc
	global_load_dwordx4 v[80:83], v[74:75], off offset:-4096
	s_lshl_b64 s[0:1], s[2:3], 13
	s_add_u32 s0, s14, s0
	s_addc_u32 s1, s15, s1
	v_lshl_add_u64 v[86:87], s[0:1], 0, v[86:87]
	s_mov_b32 s0, 0x69a81000
	s_mov_b64 s[2:3], 0x8880000
	v_pk_mul_f32 v[60:61], v[18:19], v[60:61] op_sel_hi:[0,1]
	v_pk_mul_f32 v[72:73], v[18:19], v[72:73] op_sel_hi:[0,1]
	v_pk_mul_f32 v[52:53], v[18:19], v[52:53] op_sel_hi:[0,1]
	v_pk_mul_f32 v[70:71], v[18:19], v[70:71] op_sel_hi:[0,1]
	v_pk_mul_f32 v[58:59], v[18:19], v[58:59] op_sel_hi:[0,1]
	v_pk_mul_f32 v[48:49], v[18:19], v[48:49] op_sel_hi:[0,1]
	v_pk_mul_f32 v[56:57], v[18:19], v[56:57] op_sel_hi:[0,1]
	v_pk_mul_f32 v[44:45], v[18:19], v[44:45] op_sel_hi:[0,1]
	v_pk_mul_f32 v[46:47], v[18:19], v[46:47] op_sel_hi:[0,1]
	v_pk_mul_f32 v[38:39], v[18:19], v[38:39] op_sel_hi:[0,1]
	s_waitcnt vmcnt(1)
	v_pk_fma_f32 v[76:77], v[76:77], v[28:29], v[84:85] op_sel_hi:[1,0,0]
	v_pk_fma_f32 v[28:29], v[78:79], v[28:29], v[84:85] op_sel_hi:[1,0,0]
	v_lshl_add_u64 v[84:85], v[62:63], 0, s[2:3]
	s_waitcnt vmcnt(0)
	v_pk_mul_f32 v[28:29], v[82:83], v[28:29]
	v_pk_mul_f32 v[76:77], v[80:81], v[76:77]
	s_nop 0
	v_cvt_pk_bf16_f32 v76, v76, v77
	v_cvt_pk_bf16_f32 v77, v28, v29
	v_add_co_u32_e32 v28, vcc, s0, v86
	s_mov_b64 s[0:1], 0x69980000
	s_nop 0
	v_addc_co_u32_e32 v29, vcc, 0, v87, vcc
	global_store_dwordx2 v[28:29], v[76:77], off offset:-4096
	s_waitcnt vmcnt(20)
	v_mov_b64_e32 v[76:77], v[192:193]
	v_mov_b64_e32 v[78:79], v[194:195]
	s_nop 0
	v_mov_b64_e32 v[80:81], v[196:197]
	v_mov_b64_e32 v[82:83], v[198:199]
	v_lshl_add_u64 v[90:91], v[68:69], 0, s[0:1]
	s_mov_b64 s[0:1], 0x69a80000
	v_pk_fma_f32 v[76:77], v[76:77], v[72:73], v[80:81]
	v_pk_fma_f32 v[78:79], v[78:79], v[60:61], v[82:83]
	global_store_dwordx4 v[84:85], v[76:79], off offset:1024
	s_nop 1
	v_mov_b32_e32 v72, v204
	v_mov_b32_e32 v88, v205
	v_mov_b64_e32 v[80:81], v[200:201]
	v_mov_b64_e32 v[82:83], v[202:203]
	v_add_u32_e32 v235, 0x1400, v66
	global_load_dwordx4 v[192:195], v235, s[4:5]
	global_load_dwordx4 v[196:199], v235, s[6:7]
	v_mov_b32_e32 v236, 0x50000
	global_load_dword v204, v236, s[8:9]
	global_load_dword v205, v67, s[10:11] offset:2560
	global_load_dwordx4 v[200:203], v[238:239], off offset:1024
	v_lshl_add_u64 v[60:61], v[86:87], 0, s[0:1]
	v_mov_b32_e32 v1, 0x20000
	s_mov_b32 s0, 0x8883000
	s_mov_b32 s1, 0x69983000
	v_pk_fma_f32 v[76:77], v[76:77], v[72:73], v[88:89] op_sel_hi:[1,0,0]
	v_pk_fma_f32 v[72:73], v[78:79], v[72:73], v[88:89] op_sel_hi:[1,0,0]
	v_pk_mul_f32 v[76:77], v[80:81], v[76:77]
	v_pk_mul_f32 v[72:73], v[82:83], v[72:73]
	v_cvt_pk_bf16_f32 v76, v76, v77
	s_nop 0
	v_cvt_pk_bf16_f32 v77, v72, v73
	global_store_dwordx2 v[60:61], v[76:77], off offset:512
	s_waitcnt vmcnt(22)
	v_mov_b64_e32 v[76:77], v[206:207]
	v_mov_b64_e32 v[78:79], v[208:209]
	s_nop 0
	v_mov_b64_e32 v[80:81], v[210:211]
	v_mov_b64_e32 v[82:83], v[212:213]
	v_pk_fma_f32 v[70:71], v[76:77], v[70:71], v[80:81]
	v_pk_fma_f32 v[72:73], v[78:79], v[52:53], v[82:83]
	global_store_dwordx4 v[84:85], v[70:73], off offset:2048
	s_nop 1
	v_mov_b32_e32 v52, v218
	v_mov_b32_e32 v80, v219
	v_mov_b64_e32 v[76:77], v[214:215]
	v_mov_b64_e32 v[78:79], v[216:217]
	v_add_u32_e32 v235, 0x1800, v66
	global_load_dwordx4 v[206:209], v235, s[4:5]
	global_load_dwordx4 v[210:213], v235, s[6:7]
	v_mov_b32_e32 v236, 0x60000
	global_load_dword v218, v236, s[8:9]
	global_load_dword v219, v67, s[10:11] offset:3072
	global_load_dwordx4 v[214:217], v[238:239], off offset:2048
	v_mov_b32_e32 v1, 0x30000
	v_pk_fma_f32 v[70:71], v[70:71], v[52:53], v[80:81] op_sel_hi:[1,0,0]
	v_pk_fma_f32 v[52:53], v[72:73], v[52:53], v[80:81] op_sel_hi:[1,0,0]
	v_pk_mul_f32 v[70:71], v[76:77], v[70:71]
	v_pk_mul_f32 v[52:53], v[78:79], v[52:53]
	v_cvt_pk_bf16_f32 v70, v70, v71
	s_nop 0
	v_cvt_pk_bf16_f32 v71, v52, v53
	global_store_dwordx2 v[60:61], v[70:71], off offset:1024
	s_waitcnt vmcnt(24)
	v_mov_b64_e32 v[70:71], v[220:221]
	v_mov_b64_e32 v[72:73], v[222:223]
	s_nop 0
	v_mov_b64_e32 v[76:77], v[224:225]
	v_mov_b64_e32 v[78:79], v[226:227]
	v_pk_mul_f32 v[52:53], v[18:19], v[54:55] op_sel_hi:[0,1]
	v_pk_fma_f32 v[52:53], v[70:71], v[52:53], v[76:77]
	v_pk_fma_f32 v[54:55], v[72:73], v[58:59], v[78:79]
	global_store_dwordx4 v[84:85], v[52:55], off offset:3072
	s_nop 1
	v_mov_b32_e32 v58, v232
	v_mov_b32_e32 v76, v233
	v_mov_b64_e32 v[70:71], v[228:229]
	v_mov_b64_e32 v[72:73], v[230:231]
	v_add_u32_e32 v235, 0x1c00, v66
	global_load_dwordx4 v[220:223], v235, s[4:5]
	global_load_dwordx4 v[224:227], v235, s[6:7]
	v_mov_b32_e32 v236, 0x70000
	global_load_dword v232, v236, s[8:9]
	global_load_dword v233, v67, s[10:11] offset:3584
	global_load_dwordx4 v[228:231], v[238:239], off offset:3072
	v_or_b32_e32 v1, 0x1000, v66
	v_pk_fma_f32 v[52:53], v[52:53], v[58:59], v[76:77] op_sel_hi:[1,0,0]
	v_pk_fma_f32 v[54:55], v[54:55], v[58:59], v[76:77] op_sel_hi:[1,0,0]
	v_pk_mul_f32 v[52:53], v[70:71], v[52:53]
	v_pk_mul_f32 v[54:55], v[72:73], v[54:55]
	v_cvt_pk_bf16_f32 v52, v52, v53
	s_nop 0
	v_cvt_pk_bf16_f32 v53, v54, v55
	global_store_dwordx2 v[60:61], v[52:53], off offset:1536
	s_waitcnt vmcnt(26)
	v_mov_b64_e32 v[52:53], v[178:179]
	v_mov_b64_e32 v[54:55], v[180:181]
	s_nop 0
	v_mov_b64_e32 v[70:71], v[182:183]
	v_mov_b64_e32 v[72:73], v[184:185]
	v_mov_b32_e32 v1, 0x40000
	v_pk_fma_f32 v[52:53], v[52:53], v[56:57], v[70:71]
	v_pk_fma_f32 v[54:55], v[54:55], v[48:49], v[72:73]
	global_store_dwordx4 v[64:65], v[52:55], off
	s_nop 1
	v_mov_b32_e32 v48, v190
	v_mov_b32_e32 v70, v191
	v_mov_b64_e32 v[56:57], v[186:187]
	v_mov_b64_e32 v[58:59], v[188:189]
	v_add_u32_e32 v235, 0x2000, v66
	global_load_dwordx4 v[178:181], v235, s[4:5]
	global_load_dwordx4 v[182:185], v235, s[6:7]
	v_mov_b32_e32 v236, 0x80000
	global_load_dword v190, v236, s[8:9]
	v_mov_b32_e32 v237, 0x1000
	global_load_dword v191, v237, s[10:11]
	global_load_dwordx4 v[186:189], v[240:241], off offset:-4096
	v_or_b32_e32 v1, 0x1400, v66
	v_pk_fma_f32 v[52:53], v[52:53], v[48:49], v[70:71] op_sel_hi:[1,0,0]
	v_pk_fma_f32 v[48:49], v[54:55], v[48:49], v[70:71] op_sel_hi:[1,0,0]
	v_pk_mul_f32 v[52:53], v[56:57], v[52:53]
	v_pk_mul_f32 v[48:49], v[58:59], v[48:49]
	v_cvt_pk_bf16_f32 v52, v52, v53
	s_nop 0
	v_cvt_pk_bf16_f32 v53, v48, v49
	global_store_dwordx2 v[60:61], v[52:53], off offset:2048
	s_waitcnt vmcnt(22)
	v_mov_b64_e32 v[52:53], v[192:193]
	v_mov_b64_e32 v[54:55], v[194:195]
	s_nop 0
	v_mov_b64_e32 v[56:57], v[196:197]
	v_mov_b64_e32 v[58:59], v[198:199]
	v_pk_mul_f32 v[48:49], v[18:19], v[50:51] op_sel_hi:[0,1]
	v_mov_b32_e32 v1, 0x50000
	v_pk_fma_f32 v[48:49], v[52:53], v[48:49], v[56:57]
	v_pk_fma_f32 v[50:51], v[54:55], v[44:45], v[58:59]
	global_store_dwordx4 v[64:65], v[48:51], off offset:1024
	s_nop 1
	v_mov_b32_e32 v44, v204
	v_mov_b32_e32 v56, v205
	v_mov_b64_e32 v[52:53], v[200:201]
	v_mov_b64_e32 v[54:55], v[202:203]
	v_add_u32_e32 v235, 0x2400, v66
	global_load_dwordx4 v[192:195], v235, s[4:5]
	global_load_dwordx4 v[196:199], v235, s[6:7]
	v_mov_b32_e32 v236, 0x90000
	global_load_dword v204, v236, s[8:9]
	v_mov_b32_e32 v237, 0x1200
	global_load_dword v205, v237, s[10:11]
	global_load_dwordx4 v[200:203], v[240:241], off offset:-3072
	v_or_b32_e32 v1, 0x1800, v66
	v_pk_fma_f32 v[48:49], v[48:49], v[44:45], v[56:57] op_sel_hi:[1,0,0]
	v_pk_fma_f32 v[44:45], v[50:51], v[44:45], v[56:57] op_sel_hi:[1,0,0]
	v_pk_mul_f32 v[48:49], v[52:53], v[48:49]
	v_pk_mul_f32 v[44:45], v[54:55], v[44:45]
	v_cvt_pk_bf16_f32 v48, v48, v49
	s_nop 0
	v_cvt_pk_bf16_f32 v49, v44, v45
	global_store_dwordx2 v[60:61], v[48:49], off offset:2560
	s_waitcnt vmcnt(22)
	v_mov_b64_e32 v[48:49], v[206:207]
	v_mov_b64_e32 v[50:51], v[208:209]
	s_nop 0
	v_mov_b64_e32 v[52:53], v[210:211]
	v_mov_b64_e32 v[54:55], v[212:213]
	v_mov_b32_e32 v1, 0x60000
	v_pk_fma_f32 v[44:45], v[48:49], v[38:39], v[52:53]
	v_pk_fma_f32 v[46:47], v[50:51], v[46:47], v[54:55]
	global_store_dwordx4 v[64:65], v[44:47], off offset:2048
	s_nop 1
	v_mov_b32_e32 v38, v218
	v_mov_b32_e32 v52, v219
	v_mov_b64_e32 v[48:49], v[214:215]
	v_mov_b64_e32 v[50:51], v[216:217]
	v_add_u32_e32 v235, 0x2800, v66
	global_load_dwordx4 v[206:209], v235, s[4:5]
	global_load_dwordx4 v[210:213], v235, s[6:7]
	v_mov_b32_e32 v236, 0xa0000
	global_load_dword v218, v236, s[8:9]
	v_mov_b32_e32 v237, 0x1400
	global_load_dword v219, v237, s[10:11]
	global_load_dwordx4 v[214:217], v[240:241], off offset:-2048
	v_or_b32_e32 v1, 0x1c00, v66
	v_pk_fma_f32 v[44:45], v[44:45], v[38:39], v[52:53] op_sel_hi:[1,0,0]
	v_pk_fma_f32 v[38:39], v[46:47], v[38:39], v[52:53] op_sel_hi:[1,0,0]
	v_pk_mul_f32 v[44:45], v[48:49], v[44:45]
	v_pk_mul_f32 v[38:39], v[50:51], v[38:39]
	v_cvt_pk_bf16_f32 v44, v44, v45
	s_nop 0
	v_cvt_pk_bf16_f32 v45, v38, v39
	global_store_dwordx2 v[60:61], v[44:45], off offset:3072
	s_waitcnt vmcnt(22)
	v_mov_b64_e32 v[44:45], v[220:221]
	v_mov_b64_e32 v[46:47], v[222:223]
	s_nop 0
	v_mov_b64_e32 v[48:49], v[224:225]
	v_mov_b64_e32 v[50:51], v[226:227]
	v_pk_mul_f32 v[38:39], v[18:19], v[36:37] op_sel_hi:[0,1]
	v_pk_mul_f32 v[36:37], v[18:19], v[42:43] op_sel_hi:[0,1]
	v_mov_b32_e32 v1, 0x70000
	v_mov_b32_e32 v19, 0x1000
	v_pk_mul_f32 v[32:33], v[18:19], v[32:33] op_sel_hi:[0,1]
	v_pk_mul_f32 v[34:35], v[18:19], v[34:35] op_sel_hi:[0,1]
	v_pk_mul_f32 v[26:27], v[18:19], v[26:27] op_sel_hi:[0,1]
	v_pk_mul_f32 v[16:17], v[18:19], v[16:17] op_sel_hi:[0,1]
	v_pk_mul_f32 v[14:15], v[18:19], v[14:15] op_sel_hi:[0,1]
	v_pk_mul_f32 v[12:13], v[18:19], v[12:13] op_sel_hi:[0,1]
	v_pk_mul_f32 v[10:11], v[18:19], v[10:11] op_sel_hi:[0,1]
	v_pk_mul_f32 v[8:9], v[18:19], v[8:9] op_sel_hi:[0,1]
	v_pk_mul_f32 v[6:7], v[18:19], v[6:7] op_sel_hi:[0,1]
	v_pk_mul_f32 v[4:5], v[18:19], v[4:5] op_sel_hi:[0,1]
	v_pk_mul_f32 v[2:3], v[18:19], v[2:3] op_sel_hi:[0,1]
	v_pk_fma_f32 v[36:37], v[44:45], v[36:37], v[48:49]
	v_pk_fma_f32 v[38:39], v[46:47], v[38:39], v[50:51]
	global_store_dwordx4 v[64:65], v[36:39], off offset:3072
	s_nop 1
	v_mov_b32_e32 v46, v232
	v_mov_b32_e32 v48, v233
	v_mov_b64_e32 v[42:43], v[228:229]
	v_mov_b64_e32 v[44:45], v[230:231]
	v_add_u32_e32 v235, 0x2c00, v66
	global_load_dwordx4 v[220:223], v235, s[4:5]
	global_load_dwordx4 v[224:227], v235, s[6:7]
	v_mov_b32_e32 v236, 0xb0000
	global_load_dword v232, v236, s[8:9]
	v_mov_b32_e32 v237, 0x1600
	global_load_dword v233, v237, s[10:11]
	global_load_dwordx4 v[228:231], v[240:241], off offset:-1024
	v_or_b32_e32 v1, 0x2000, v66
	v_pk_fma_f32 v[36:37], v[36:37], v[46:47], v[48:49] op_sel_hi:[1,0,0]
	v_pk_fma_f32 v[38:39], v[38:39], v[46:47], v[48:49] op_sel_hi:[1,0,0]
	v_pk_mul_f32 v[36:37], v[42:43], v[36:37]
	v_pk_mul_f32 v[38:39], v[44:45], v[38:39]
	v_cvt_pk_bf16_f32 v36, v36, v37
	s_nop 0
	v_cvt_pk_bf16_f32 v37, v38, v39
	global_store_dwordx2 v[60:61], v[36:37], off offset:3584
	s_waitcnt vmcnt(22)
	v_mov_b64_e32 v[42:43], v[178:179]
	v_mov_b64_e32 v[44:45], v[180:181]
	v_mov_b64_e32 v[46:47], v[182:183]
	v_mov_b64_e32 v[48:49], v[184:185]
	v_add_co_u32_e32 v36, vcc, s0, v62
	v_pk_mul_f32 v[38:39], v[18:19], v[40:41] op_sel_hi:[0,1]
	s_nop 0
	v_addc_co_u32_e32 v37, vcc, 0, v63, vcc
	v_mov_b32_e32 v1, 0x80000
	s_mov_b32 s0, 0x8882000
	v_pk_fma_f32 v[38:39], v[42:43], v[38:39], v[46:47]
	v_pk_fma_f32 v[40:41], v[44:45], v[32:33], v[48:49]
	global_store_dwordx4 v[36:37], v[38:41], off offset:-4096
	v_add_co_u32_e32 v32, vcc, s1, v68
	s_nop 1
	v_mov_b32_e32 v46, v190
	v_mov_b32_e32 v48, v191
	v_addc_co_u32_e32 v33, vcc, 0, v69, vcc
	v_mov_b64_e32 v[42:43], v[186:187]
	v_mov_b64_e32 v[44:45], v[188:189]
	v_add_u32_e32 v235, 0x3000, v66
	global_load_dwordx4 v[178:181], v235, s[4:5]
	global_load_dwordx4 v[182:185], v235, s[6:7]
	v_mov_b32_e32 v236, 0xc0000
	global_load_dword v190, v236, s[8:9]
	v_mov_b32_e32 v237, 0x1800
	global_load_dword v191, v237, s[10:11]
	global_load_dwordx4 v[186:189], v[240:241], off offset:0
	v_or_b32_e32 v1, 0x2400, v66
	s_mov_b32 s1, 0x69982000
	v_pk_fma_f32 v[38:39], v[38:39], v[46:47], v[48:49] op_sel_hi:[1,0,0]
	v_pk_fma_f32 v[40:41], v[40:41], v[46:47], v[48:49] op_sel_hi:[1,0,0]
	v_add_co_u32_e32 v46, vcc, s0, v62
	v_pk_mul_f32 v[38:39], v[42:43], v[38:39]
	v_pk_mul_f32 v[40:41], v[44:45], v[40:41]
	v_cvt_pk_bf16_f32 v38, v38, v39
	v_addc_co_u32_e32 v47, vcc, 0, v63, vcc
	v_cvt_pk_bf16_f32 v39, v40, v41
	global_store_dwordx2 v[28:29], v[38:39], off
	s_waitcnt vmcnt(22)
	v_mov_b64_e32 v[38:39], v[192:193]
	v_mov_b64_e32 v[40:41], v[194:195]
	s_nop 0
	v_mov_b64_e32 v[42:43], v[196:197]
	v_mov_b64_e32 v[44:45], v[198:199]
	v_mov_b32_e32 v1, 0x90000
	v_add_co_u32_e32 v48, vcc, s1, v68
	v_pk_fma_f32 v[38:39], v[38:39], v[26:27], v[42:43]
	v_pk_fma_f32 v[40:41], v[40:41], v[34:35], v[44:45]
	global_store_dwordx4 v[46:47], v[38:41], off offset:1024
	s_nop 1
	v_mov_b32_e32 v26, v204
	v_mov_b32_e32 v34, v205
	v_addc_co_u32_e32 v49, vcc, 0, v69, vcc
	v_mov_b64_e32 v[42:43], v[200:201]
	v_mov_b64_e32 v[44:45], v[202:203]
	v_add_u32_e32 v235, 0x3400, v66
	global_load_dwordx4 v[192:195], v235, s[4:5]
	global_load_dwordx4 v[196:199], v235, s[6:7]
	v_mov_b32_e32 v236, 0xd0000
	global_load_dword v204, v236, s[8:9]
	v_mov_b32_e32 v237, 0x1a00
	global_load_dword v205, v237, s[10:11]
	global_load_dwordx4 v[200:203], v[240:241], off offset:1024
	v_or_b32_e32 v1, 0x2800, v66
	v_pk_fma_f32 v[38:39], v[38:39], v[26:27], v[34:35] op_sel_hi:[1,0,0]
	v_pk_fma_f32 v[26:27], v[40:41], v[26:27], v[34:35] op_sel_hi:[1,0,0]
	v_pk_mul_f32 v[34:35], v[42:43], v[38:39]
	v_pk_mul_f32 v[26:27], v[44:45], v[26:27]
	v_cvt_pk_bf16_f32 v34, v34, v35
	s_nop 0
	v_cvt_pk_bf16_f32 v35, v26, v27
	global_store_dwordx2 v[28:29], v[34:35], off offset:512
	s_waitcnt vmcnt(22)
	v_mov_b64_e32 v[38:39], v[206:207]
	v_mov_b64_e32 v[40:41], v[208:209]
	v_mov_b64_e32 v[42:43], v[210:211]
	v_mov_b64_e32 v[44:45], v[212:213]
	v_pk_mul_f32 v[26:27], v[18:19], v[24:25] op_sel_hi:[0,1]
	v_pk_mul_f32 v[24:25], v[18:19], v[30:31] op_sel_hi:[0,1]
	v_mov_b32_e32 v1, 0xa0000
	v_pk_fma_f32 v[24:25], v[38:39], v[24:25], v[42:43]
	v_pk_fma_f32 v[26:27], v[40:41], v[26:27], v[44:45]
	global_store_dwordx4 v[46:47], v[24:27], off offset:2048
	s_nop 1
	v_mov_b32_e32 v30, v218
	v_mov_b32_e32 v34, v219
	v_mov_b64_e32 v[38:39], v[214:215]
	v_mov_b64_e32 v[40:41], v[216:217]
	v_add_u32_e32 v235, 0x3800, v66
	global_load_dwordx4 v[206:209], v235, s[4:5]
	global_load_dwordx4 v[210:213], v235, s[6:7]
	v_mov_b32_e32 v236, 0xe0000
	global_load_dword v218, v236, s[8:9]
	v_mov_b32_e32 v237, 0x1c00
	global_load_dword v219, v237, s[10:11]
	global_load_dwordx4 v[214:217], v[240:241], off offset:2048
	v_or_b32_e32 v1, 0x2c00, v66
	v_pk_fma_f32 v[24:25], v[24:25], v[30:31], v[34:35] op_sel_hi:[1,0,0]
	v_pk_fma_f32 v[26:27], v[26:27], v[30:31], v[34:35] op_sel_hi:[1,0,0]
	v_pk_mul_f32 v[24:25], v[38:39], v[24:25]
	v_pk_mul_f32 v[26:27], v[40:41], v[26:27]
	v_cvt_pk_bf16_f32 v24, v24, v25
	v_pk_mul_f32 v[30:31], v[18:19], v[20:21] op_sel_hi:[0,1]
	v_cvt_pk_bf16_f32 v25, v26, v27
	global_store_dwordx2 v[28:29], v[24:25], off offset:1024
	s_waitcnt vmcnt(22)
	v_mov_b64_e32 v[24:25], v[220:221]
	v_mov_b64_e32 v[26:27], v[222:223]
	s_nop 0
	v_mov_b64_e32 v[38:39], v[224:225]
	v_mov_b64_e32 v[40:41], v[226:227]
	v_pk_mul_f32 v[20:21], v[18:19], v[22:23] op_sel_hi:[0,1]
	v_mov_b32_e32 v1, 0xb0000
	v_pk_fma_f32 v[20:21], v[24:25], v[20:21], v[38:39]
	v_pk_fma_f32 v[22:23], v[26:27], v[30:31], v[40:41]
	global_store_dwordx4 v[46:47], v[20:23], off offset:3072
	s_nop 1
	v_mov_b32_e32 v30, v232
	v_mov_b32_e32 v34, v233
	v_mov_b64_e32 v[24:25], v[228:229]
	v_mov_b64_e32 v[26:27], v[230:231]
	v_add_u32_e32 v235, 0x3c00, v66
	global_load_dwordx4 v[220:223], v235, s[4:5]
	global_load_dwordx4 v[224:227], v235, s[6:7]
	v_mov_b32_e32 v236, 0xf0000
	global_load_dword v232, v236, s[8:9]
	v_mov_b32_e32 v237, 0x1e00
	global_load_dword v233, v237, s[10:11]
	global_load_dwordx4 v[228:231], v[240:241], off offset:3072
	v_or_b32_e32 v1, 0x3000, v66
	v_pk_fma_f32 v[20:21], v[20:21], v[30:31], v[34:35] op_sel_hi:[1,0,0]
	v_pk_fma_f32 v[22:23], v[22:23], v[30:31], v[34:35] op_sel_hi:[1,0,0]
	v_pk_mul_f32 v[20:21], v[24:25], v[20:21]
	v_pk_mul_f32 v[22:23], v[26:27], v[22:23]
	v_cvt_pk_bf16_f32 v20, v20, v21
	s_nop 0
	v_cvt_pk_bf16_f32 v21, v22, v23
	global_store_dwordx2 v[28:29], v[20:21], off offset:1536
	s_waitcnt vmcnt(22)
	v_mov_b64_e32 v[20:21], v[178:179]
	v_mov_b64_e32 v[22:23], v[180:181]
	s_nop 0
	v_mov_b64_e32 v[24:25], v[182:183]
	v_mov_b64_e32 v[26:27], v[184:185]
	v_mov_b32_e32 v1, 0xc0000
	v_pk_fma_f32 v[14:15], v[20:21], v[14:15], v[24:25]
	v_pk_fma_f32 v[16:17], v[22:23], v[16:17], v[26:27]
	global_store_dwordx4 v[36:37], v[14:17], off
	s_nop 1
	v_mov_b32_e32 v24, v190
	v_mov_b32_e32 v26, v191
	v_mov_b64_e32 v[20:21], v[186:187]
	v_mov_b64_e32 v[22:23], v[188:189]
	v_or_b32_e32 v1, 0x3400, v66
	v_pk_fma_f32 v[14:15], v[14:15], v[24:25], v[26:27] op_sel_hi:[1,0,0]
	v_pk_fma_f32 v[16:17], v[16:17], v[24:25], v[26:27] op_sel_hi:[1,0,0]
	v_pk_mul_f32 v[14:15], v[20:21], v[14:15]
	v_pk_mul_f32 v[16:17], v[22:23], v[16:17]
	v_cvt_pk_bf16_f32 v14, v14, v15
	s_nop 0
	v_cvt_pk_bf16_f32 v15, v16, v17
	global_store_dwordx2 v[28:29], v[14:15], off offset:2048
	s_waitcnt vmcnt(17)
	v_mov_b64_e32 v[14:15], v[192:193]
	v_mov_b64_e32 v[16:17], v[194:195]
	s_nop 0
	v_mov_b64_e32 v[20:21], v[196:197]
	v_mov_b64_e32 v[22:23], v[198:199]
	v_mov_b32_e32 v1, 0xd0000
	v_pk_fma_f32 v[10:11], v[14:15], v[10:11], v[20:21]
	v_pk_fma_f32 v[12:13], v[16:17], v[12:13], v[22:23]
	global_store_dwordx4 v[36:37], v[10:13], off offset:1024
	s_nop 1
	v_mov_b32_e32 v20, v204
	v_mov_b32_e32 v22, v205
	v_mov_b64_e32 v[14:15], v[200:201]
	v_mov_b64_e32 v[16:17], v[202:203]
	v_or_b32_e32 v1, 0x3800, v66
	v_pk_fma_f32 v[10:11], v[10:11], v[20:21], v[22:23] op_sel_hi:[1,0,0]
	v_pk_fma_f32 v[12:13], v[12:13], v[20:21], v[22:23] op_sel_hi:[1,0,0]
	v_pk_mul_f32 v[10:11], v[14:15], v[10:11]
	v_pk_mul_f32 v[12:13], v[16:17], v[12:13]
	v_cvt_pk_bf16_f32 v10, v10, v11
	s_nop 0
	v_cvt_pk_bf16_f32 v11, v12, v13
	global_store_dwordx2 v[28:29], v[10:11], off offset:2560
	s_waitcnt vmcnt(12)
	v_mov_b64_e32 v[10:11], v[206:207]
	v_mov_b64_e32 v[12:13], v[208:209]
	s_nop 0
	v_mov_b64_e32 v[14:15], v[210:211]
	v_mov_b64_e32 v[16:17], v[212:213]
	v_mov_b32_e32 v1, 0xe0000
	v_pk_fma_f32 v[6:7], v[10:11], v[6:7], v[14:15]
	v_pk_fma_f32 v[8:9], v[12:13], v[8:9], v[16:17]
	global_store_dwordx4 v[36:37], v[6:9], off offset:2048
	s_nop 1
	v_mov_b32_e32 v14, v218
	v_mov_b32_e32 v16, v219
	v_mov_b64_e32 v[10:11], v[214:215]
	v_mov_b64_e32 v[12:13], v[216:217]
	v_or_b32_e32 v1, 0x3c00, v66
	v_pk_fma_f32 v[6:7], v[6:7], v[14:15], v[16:17] op_sel_hi:[1,0,0]
	v_pk_fma_f32 v[8:9], v[8:9], v[14:15], v[16:17] op_sel_hi:[1,0,0]
	v_pk_mul_f32 v[6:7], v[10:11], v[6:7]
	v_pk_mul_f32 v[8:9], v[12:13], v[8:9]
	v_cvt_pk_bf16_f32 v6, v6, v7
	s_nop 0
	v_cvt_pk_bf16_f32 v7, v8, v9
	global_store_dwordx2 v[28:29], v[6:7], off offset:3072
	s_waitcnt vmcnt(7)
	v_mov_b64_e32 v[6:7], v[220:221]
	v_mov_b64_e32 v[8:9], v[222:223]
	s_nop 0
	v_mov_b64_e32 v[10:11], v[224:225]
	v_mov_b64_e32 v[12:13], v[226:227]
	v_mov_b32_e32 v1, 0xf0000
	v_pk_fma_f32 v[2:3], v[6:7], v[2:3], v[10:11]
	v_pk_fma_f32 v[4:5], v[8:9], v[4:5], v[12:13]
	global_store_dwordx4 v[36:37], v[2:5], off offset:3072
	s_nop 1
	v_mov_b32_e32 v10, v232
	v_mov_b32_e32 v12, v233
	v_mov_b64_e32 v[6:7], v[228:229]
	v_mov_b64_e32 v[8:9], v[230:231]
	v_pk_fma_f32 v[2:3], v[2:3], v[10:11], v[12:13] op_sel_hi:[1,0,0]
	v_pk_fma_f32 v[4:5], v[4:5], v[10:11], v[12:13] op_sel_hi:[1,0,0]
	v_pk_mul_f32 v[2:3], v[6:7], v[2:3]
	v_pk_mul_f32 v[4:5], v[8:9], v[4:5]
	v_cvt_pk_bf16_f32 v2, v2, v3
	s_nop 0
	v_cvt_pk_bf16_f32 v3, v4, v5
	global_store_dwordx2 v[28:29], v[2:3], off offset:3584
